# EpiSoftmax rstd batching: cross-score epilogue computes the 8 per-row rstd once in a batch (was a serialized ssq load + 2 shuffles per row in both passes)
# speedup vs baseline: 1.0211x; 1.0119x over previous
; __device__ __forceinline__ float row_rstd(const float* ssq, int row, int fq) {
;     const f32x4 v = *(const f32x4*)(ssq + (size_t)row * 16 + fq * 4);
;     float s = (v[0] + v[1]) + (v[2] + v[3]);
;     s += __shfl_xor(s, 16); s += __shfl_xor(s, 32);
;     return __builtin_amdgcn_rsqf(s * (1.f / DM) + EPS);
; }
;     __device__ __forceinline__ void operator()(const f32x4 (&acc_)[2][2][4][2], const pg8::Unit& u, int wr, int wc, int fr, int fq) const {
;     ...
;         const int row0 = u.pm * 256 + wr * 64 + fr, lrow0 = wr * 64 + fr;
; #pragma unroll
;         for (int ai = 0; ai < 2; ++ai)
; #pragma unroll
;             for (int m = 0; m < 4; ++m) { const float rs = row_rstd(ssq, row0 + ai * 128 + m * 16, fq); float mx = -3.0e38f;
; #pragma unroll
;                 for (int bj = 0; bj < 2; ++bj)
; #pragma unroll
;                     for (int n = 0; n < 2; ++n) { const f32x4 a = acc[ai][bj][m][n]; mx = fmaxf(mx, fmaxf(fmaxf(a[0], a[1]), fmaxf(a[2], a[3]))); }
;                 mx *= rs; mx = fmaxf(mx, __shfl_xor(mx, 16)); mx = fmaxf(mx, __shfl_xor(mx, 32));
;                 if (fq == 0) xch[(lrow0 + ai * 128 + m * 16) * 4 + wc] = mx; }
.LBB0_998:
	v_lshl_add_u32 v228, s24, 8, v174
	v_mov_b32_e32 v144, v228
	v_ashrrev_i32_e32 v145, 31, v144
	v_lshlrev_b64 v[144:145], 6, v[144:145]
	v_lshl_add_u64 v[144:145], v[136:137], 0, v[144:145]
	global_load_dwordx4 v[144:147], v[144:145], off
	v_add_u32_e32 v148, 16, v228
	v_ashrrev_i32_e32 v149, 31, v148
	v_lshlrev_b64 v[148:149], 6, v[148:149]
	v_lshl_add_u64 v[148:149], v[136:137], 0, v[148:149]
	global_load_dwordx4 v[148:151], v[148:149], off
	v_add_u32_e32 v152, 32, v228
	v_ashrrev_i32_e32 v153, 31, v152
	v_lshlrev_b64 v[152:153], 6, v[152:153]
	v_lshl_add_u64 v[152:153], v[136:137], 0, v[152:153]
	global_load_dwordx4 v[152:155], v[152:153], off
	v_add_u32_e32 v156, 48, v228
	v_ashrrev_i32_e32 v157, 31, v156
	v_lshlrev_b64 v[156:157], 6, v[156:157]
	v_lshl_add_u64 v[156:157], v[136:137], 0, v[156:157]
	global_load_dwordx4 v[156:159], v[156:157], off
	v_add_u32_e32 v160, 0x80, v228
	v_ashrrev_i32_e32 v161, 31, v160
	v_lshlrev_b64 v[160:161], 6, v[160:161]
	v_lshl_add_u64 v[160:161], v[136:137], 0, v[160:161]
	global_load_dwordx4 v[160:163], v[160:161], off
	v_add_u32_e32 v164, 0x90, v228
	v_ashrrev_i32_e32 v165, 31, v164
	v_lshlrev_b64 v[164:165], 6, v[164:165]
	v_lshl_add_u64 v[164:165], v[136:137], 0, v[164:165]
	global_load_dwordx4 v[164:167], v[164:165], off
	v_add_u32_e32 v168, 0xa0, v228
	v_ashrrev_i32_e32 v169, 31, v168
	v_lshlrev_b64 v[168:169], 6, v[168:169]
	v_lshl_add_u64 v[168:169], v[136:137], 0, v[168:169]
	global_load_dwordx4 v[168:171], v[168:169], off
	v_add_u32_e32 v222, 0xb0, v228
	v_ashrrev_i32_e32 v223, 31, v222
	v_lshlrev_b64 v[222:223], 6, v[222:223]
	v_lshl_add_u64 v[222:223], v[136:137], 0, v[222:223]
	global_load_dwordx4 v[222:225], v[222:223], off
	v_xor_b32_e32 v226, 16, v215
	v_xor_b32_e32 v227, 32, v215
	v_lshlrev_b32_e32 v226, 2, v226
	v_lshlrev_b32_e32 v227, 2, v227
	s_waitcnt vmcnt(0)
	v_add_f32_e32 v144, v144, v145
	v_add_f32_e32 v146, v146, v147
	v_add_f32_e32 v148, v148, v149
	v_add_f32_e32 v150, v150, v151
	v_add_f32_e32 v152, v152, v153
	v_add_f32_e32 v154, v154, v155
	v_add_f32_e32 v156, v156, v157
	v_add_f32_e32 v158, v158, v159
	v_add_f32_e32 v160, v160, v161
	v_add_f32_e32 v162, v162, v163
	v_add_f32_e32 v164, v164, v165
	v_add_f32_e32 v166, v166, v167
	v_add_f32_e32 v168, v168, v169
	v_add_f32_e32 v170, v170, v171
	v_add_f32_e32 v222, v222, v223
	v_add_f32_e32 v224, v224, v225
	v_add_f32_e32 v144, v144, v146
	v_add_f32_e32 v148, v148, v150
	v_add_f32_e32 v152, v152, v154
	v_add_f32_e32 v156, v156, v158
	v_add_f32_e32 v160, v160, v162
	v_add_f32_e32 v164, v164, v166
	v_add_f32_e32 v168, v168, v170
	v_add_f32_e32 v222, v222, v224
	ds_bpermute_b32 v145, v226, v144
	ds_bpermute_b32 v149, v226, v148
	ds_bpermute_b32 v153, v226, v152
	ds_bpermute_b32 v157, v226, v156
	ds_bpermute_b32 v161, v226, v160
	ds_bpermute_b32 v165, v226, v164
	ds_bpermute_b32 v169, v226, v168
	ds_bpermute_b32 v223, v226, v222
	s_waitcnt lgkmcnt(0)
	v_add_f32_e32 v144, v144, v145
	v_add_f32_e32 v148, v148, v149
	v_add_f32_e32 v152, v152, v153
	v_add_f32_e32 v156, v156, v157
	v_add_f32_e32 v160, v160, v161
	v_add_f32_e32 v164, v164, v165
	v_add_f32_e32 v168, v168, v169
	v_add_f32_e32 v222, v222, v223
	ds_bpermute_b32 v145, v227, v144
	ds_bpermute_b32 v149, v227, v148
	ds_bpermute_b32 v153, v227, v152
	ds_bpermute_b32 v157, v227, v156
	ds_bpermute_b32 v161, v227, v160
	ds_bpermute_b32 v165, v227, v164
	ds_bpermute_b32 v169, v227, v168
	ds_bpermute_b32 v223, v227, v222
	s_waitcnt lgkmcnt(0)
	v_add_f32_e32 v144, v144, v145
	v_add_f32_e32 v148, v148, v149
	v_add_f32_e32 v152, v152, v153
	v_add_f32_e32 v156, v156, v157
	v_add_f32_e32 v160, v160, v161
	v_add_f32_e32 v164, v164, v165
	v_add_f32_e32 v168, v168, v169
	v_add_f32_e32 v222, v222, v223
	v_fmamk_f32 v144, v144, 0x3a800000, v212
	v_fmamk_f32 v148, v148, 0x3a800000, v212
	v_fmamk_f32 v152, v152, 0x3a800000, v212
	v_fmamk_f32 v156, v156, 0x3a800000, v212
	v_fmamk_f32 v160, v160, 0x3a800000, v212
	v_fmamk_f32 v164, v164, 0x3a800000, v212
	v_fmamk_f32 v168, v168, 0x3a800000, v212
	v_fmamk_f32 v222, v222, 0x3a800000, v212
	v_rsq_f32_e32 v246, v144
	v_rsq_f32_e32 v247, v148
	v_rsq_f32_e32 v248, v152
	v_rsq_f32_e32 v249, v156
	v_rsq_f32_e32 v250, v160
	v_rsq_f32_e32 v251, v164
	v_rsq_f32_e32 v252, v168
	v_rsq_f32_e32 v253, v222
	s_nop 0
	v_and_b32_e32 v144, 64, v215
	v_xor_b32_e32 v143, 16, v215
	v_add_u32_e32 v144, 64, v144
	v_cmp_lt_i32_e32 vcc, v143, v144
	v_lshl_add_u32 v142, s24, 8, v174
	s_mov_b32 s2, 0xff61b1e6
	v_cndmask_b32_e32 v143, v215, v143, vcc
	v_lshlrev_b32_e32 v209, 2, v143
	v_xor_b32_e32 v143, 32, v215
	v_cmp_lt_i32_e32 vcc, v143, v144
	v_max_f32_e32 v148, v114, v114
	v_add_u32_e32 v210, s74, v176
	v_cndmask_b32_e32 v143, v215, v143, vcc
	v_lshlrev_b32_e32 v208, 2, v143
	v_ashrrev_i32_e32 v143, 31, v142
	v_lshlrev_b64 v[144:145], 6, v[142:143]
	v_lshl_add_u64 v[158:159], v[136:137], 0, v[144:145]
	s_nop 0
	s_waitcnt lgkmcnt(0)
	s_nop 0
	s_nop 0
	s_nop 0
	s_nop 0
	v_max_f32_e32 v146, v126, v126
	v_max_f32_e32 v147, v122, v122
	s_waitcnt lgkmcnt(0)
	s_nop 0
	s_nop 0
	s_waitcnt lgkmcnt(0)
	s_nop 0
	v_max_f32_e32 v145, v127, v127
	v_max_f32_e32 v145, v146, v145
	v_max_f32_e32 v146, v123, v123
	v_max_f32_e32 v146, v147, v146
	v_max3_f32 v145, v124, v125, v145
	v_max3_f32 v146, v120, v121, v146
	s_nop 0
	v_max3_f32 v145, v145, s2, v146
	v_max_f32_e32 v146, v119, v119
	v_max_f32_e32 v147, v118, v118
	v_max_f32_e32 v146, v147, v146
	v_max_f32_e32 v147, v115, v115
	v_mov_b32_e32 v144, v246
	v_max_f32_e32 v147, v148, v147
	v_max3_f32 v146, v116, v117, v146
	v_max3_f32 v147, v112, v113, v147
	v_max3_f32 v145, v145, v146, v147
	v_mul_f32_e32 v144, v145, v144
	ds_bpermute_b32 v145, v209, v144
	s_waitcnt lgkmcnt(0)
	v_max_f32_e32 v145, v145, v145
	v_max_f32_e32 v144, v144, v145
	ds_bpermute_b32 v145, v208, v144
	s_and_saveexec_b64 s[24:25], s[4:5]
	s_cbranch_execz .LBB0_1000
	s_waitcnt lgkmcnt(0)
	v_max_f32_e32 v145, v145, v145
	v_max_f32_e32 v144, v144, v144
	v_max_f32_e32 v144, v144, v145
	ds_write_b32 v210, v144
;     __device__ __forceinline__ void operator()(const f32x4 (&acc_)[2][2][4][2], const pg8::Unit& u, int wr, int wc, int fr, int fq) const {
;     ...
;             for (int m = 0; m < 4; ++m) { const float rs = row_rstd(ssq, row0 + ai * 128 + m * 16, fq); float mx = -3.0e38f;
; #pragma unroll
;                 for (int bj = 0; bj < 2; ++bj)
; #pragma unroll
;                     for (int n = 0; n < 2; ++n) { const f32x4 a = acc[ai][bj][m][n]; mx = fmaxf(mx, fmaxf(fmaxf(a[0], a[1]), fmaxf(a[2], a[3]))); }
;                 mx *= rs; mx = fmaxf(mx, __shfl_xor(mx, 16)); mx = fmaxf(mx, __shfl_xor(mx, 32));
;                 if (fq == 0) xch[(lrow0 + ai * 128 + m * 16) * 4 + wc] = mx; }
.LBB0_1000:
	s_or_b64 exec, exec, s[24:25]
	v_or_b32_e32 v144, 16, v142
	s_waitcnt lgkmcnt(0)
	v_ashrrev_i32_e32 v145, 31, v144
	v_lshlrev_b64 v[146:147], 6, v[144:145]
	v_lshl_add_u64 v[160:161], v[136:137], 0, v[146:147]
	s_nop 0
	v_max_f32_e32 v150, v98, v98
	s_waitcnt lgkmcnt(0)
	s_nop 0
	s_nop 0
	s_nop 0
	s_nop 0
	v_max_f32_e32 v148, v110, v110
	v_max_f32_e32 v149, v106, v106
	s_waitcnt lgkmcnt(0)
	s_nop 0
	s_nop 0
	s_waitcnt lgkmcnt(0)
	s_nop 0
	v_max_f32_e32 v147, v111, v111
	v_max_f32_e32 v147, v148, v147
	v_max_f32_e32 v148, v107, v107
	v_max_f32_e32 v148, v149, v148
	v_max3_f32 v147, v108, v109, v147
	v_max3_f32 v148, v104, v105, v148
	s_nop 0
	v_max3_f32 v147, v147, s2, v148
	v_max_f32_e32 v148, v103, v103
	v_max_f32_e32 v149, v102, v102
	v_max_f32_e32 v148, v149, v148
	v_max_f32_e32 v149, v99, v99
	v_mov_b32_e32 v146, v247
	v_max_f32_e32 v149, v150, v149
	v_max3_f32 v148, v100, v101, v148
	v_max3_f32 v149, v96, v97, v149
	v_max3_f32 v147, v147, v148, v149
	v_mul_f32_e32 v146, v147, v146
	ds_bpermute_b32 v147, v209, v146
	s_waitcnt lgkmcnt(0)
	v_max_f32_e32 v147, v147, v147
	v_max_f32_e32 v146, v146, v147
	ds_bpermute_b32 v147, v208, v146
	s_and_saveexec_b64 s[24:25], s[4:5]
	s_cbranch_execz .LBB0_1002
	s_waitcnt lgkmcnt(0)
	v_max_f32_e32 v147, v147, v147
	v_max_f32_e32 v146, v146, v146
	v_max_f32_e32 v146, v146, v147
	ds_write_b32 v210, v146 offset:256
.LBB0_1002:
	s_or_b64 exec, exec, s[24:25]
	v_or_b32_e32 v146, 32, v142
	s_waitcnt lgkmcnt(0)
	v_ashrrev_i32_e32 v147, 31, v146
	v_lshlrev_b64 v[148:149], 6, v[146:147]
	v_lshl_add_u64 v[162:163], v[136:137], 0, v[148:149]
	s_nop 0
	v_max_f32_e32 v152, v82, v82
	s_waitcnt lgkmcnt(0)
	s_nop 0
	s_nop 0
	s_nop 0
	s_nop 0
	v_max_f32_e32 v150, v94, v94
	v_max_f32_e32 v151, v90, v90
	s_waitcnt lgkmcnt(0)
	s_nop 0
	s_nop 0
	s_waitcnt lgkmcnt(0)
	s_nop 0
	v_max_f32_e32 v149, v95, v95
	v_max_f32_e32 v149, v150, v149
	v_max_f32_e32 v150, v91, v91
	v_max_f32_e32 v150, v151, v150
	v_max3_f32 v149, v92, v93, v149
	v_max3_f32 v150, v88, v89, v150
	s_nop 0
	v_max3_f32 v149, v149, s2, v150
	v_max_f32_e32 v150, v87, v87
	v_max_f32_e32 v151, v86, v86
	v_max_f32_e32 v150, v151, v150
	v_max_f32_e32 v151, v83, v83
	v_mov_b32_e32 v148, v248
	v_max_f32_e32 v151, v152, v151
	v_max3_f32 v150, v84, v85, v150
	v_max3_f32 v151, v80, v81, v151
	v_max3_f32 v149, v149, v150, v151
	v_mul_f32_e32 v148, v149, v148
	ds_bpermute_b32 v149, v209, v148
	s_waitcnt lgkmcnt(0)
	v_max_f32_e32 v149, v149, v149
	v_max_f32_e32 v148, v148, v149
	ds_bpermute_b32 v149, v208, v148
	s_mov_b64 s[24:25], exec
	s_and_b64 s[26:27], s[24:25], s[4:5]
	v_mov_b64_e32 v[242:243], v[196:197]
	v_mov_b64_e32 v[196:197], v[198:199]
	v_mov_b64_e32 v[198:199], v[200:201]
	v_mov_b64_e32 v[200:201], v[178:179]
	s_mov_b64 exec, s[26:27]
	s_cbranch_execz .LBB0_1004
	s_waitcnt lgkmcnt(0)
	v_max_f32_e32 v149, v149, v149
	v_max_f32_e32 v148, v148, v148
	v_max_f32_e32 v148, v148, v149
	ds_write_b32 v210, v148 offset:512
.LBB0_1004:
	s_or_b64 exec, exec, s[24:25]
	v_or_b32_e32 v148, 48, v142
	s_waitcnt lgkmcnt(0)
	v_ashrrev_i32_e32 v149, 31, v148
	v_lshlrev_b64 v[150:151], 6, v[148:149]
	v_lshl_add_u64 v[164:165], v[136:137], 0, v[150:151]
	s_nop 0
	v_max_f32_e32 v154, v66, v66
	s_waitcnt lgkmcnt(0)
	s_nop 0
	s_nop 0
	s_nop 0
	s_nop 0
	v_max_f32_e32 v152, v78, v78
	v_max_f32_e32 v153, v74, v74
	s_waitcnt lgkmcnt(0)
	s_nop 0
	s_nop 0
	s_waitcnt lgkmcnt(0)
	s_nop 0
	v_max_f32_e32 v151, v79, v79
	v_max_f32_e32 v151, v152, v151
	v_max_f32_e32 v152, v75, v75
	v_max_f32_e32 v152, v153, v152
	v_max3_f32 v151, v76, v77, v151
	v_max3_f32 v152, v72, v73, v152
	s_nop 0
	v_max3_f32 v151, v151, s2, v152
	v_max_f32_e32 v152, v71, v71
	v_max_f32_e32 v153, v70, v70
	v_max_f32_e32 v152, v153, v152
	v_max_f32_e32 v153, v67, v67
	v_mov_b32_e32 v150, v249
	v_max_f32_e32 v153, v154, v153
	v_max3_f32 v152, v68, v69, v152
	v_max3_f32 v153, v64, v65, v153
	v_max3_f32 v151, v151, v152, v153
	v_mul_f32_e32 v150, v151, v150
	ds_bpermute_b32 v151, v209, v150
	s_waitcnt lgkmcnt(0)
	v_max_f32_e32 v151, v151, v151
	v_max_f32_e32 v150, v150, v151
	ds_bpermute_b32 v151, v208, v150
	s_and_saveexec_b64 s[24:25], s[4:5]
	s_cbranch_execz .LBB0_1006
	s_waitcnt lgkmcnt(0)
	v_max_f32_e32 v151, v151, v151
	v_max_f32_e32 v150, v150, v150
	v_max_f32_e32 v150, v150, v151
	ds_write_b32 v210, v150 offset:768
.LBB0_1006:
	s_or_b64 exec, exec, s[24:25]
	v_add_u32_e32 v150, 0x80, v142
	s_waitcnt lgkmcnt(0)
	v_ashrrev_i32_e32 v151, 31, v150
	v_lshlrev_b64 v[152:153], 6, v[150:151]
	v_lshl_add_u64 v[166:167], v[136:137], 0, v[152:153]
	s_nop 0
	v_max_f32_e32 v156, v50, v50
	s_waitcnt lgkmcnt(0)
	s_nop 0
	s_nop 0
	s_nop 0
	s_nop 0
	v_max_f32_e32 v154, v62, v62
	v_max_f32_e32 v155, v58, v58
	s_waitcnt lgkmcnt(0)
	s_nop 0
	s_nop 0
	s_waitcnt lgkmcnt(0)
	s_nop 0
	v_max_f32_e32 v153, v63, v63
	v_max_f32_e32 v153, v154, v153
	v_max_f32_e32 v154, v59, v59
	v_max_f32_e32 v154, v155, v154
	v_max3_f32 v153, v60, v61, v153
	v_max3_f32 v154, v56, v57, v154
	s_nop 0
	v_max3_f32 v153, v153, s2, v154
	v_max_f32_e32 v154, v55, v55
	v_max_f32_e32 v155, v54, v54
	v_max_f32_e32 v154, v155, v154
	v_max_f32_e32 v155, v51, v51
	v_mov_b32_e32 v152, v250
	v_max_f32_e32 v155, v156, v155
	v_max3_f32 v154, v52, v53, v154
	v_max3_f32 v155, v48, v49, v155
	v_max3_f32 v153, v153, v154, v155
	v_mul_f32_e32 v152, v153, v152
	ds_bpermute_b32 v153, v209, v152
	s_waitcnt lgkmcnt(0)
	v_max_f32_e32 v153, v153, v153
	v_max_f32_e32 v152, v152, v153
	ds_bpermute_b32 v153, v208, v152
	s_and_saveexec_b64 s[24:25], s[4:5]
	s_cbranch_execz .LBB0_1008
	s_waitcnt lgkmcnt(0)
	v_max_f32_e32 v153, v153, v153
	v_max_f32_e32 v152, v152, v152
	v_max_f32_e32 v152, v152, v153
	ds_write_b32 v210, v152 offset:2048
; #define LAS __attribute__((address_space(3)))
;     __device__ __forceinline__ void operator()(const f32x4 (&acc_)[2][2][4][2], const pg8::Unit& u, int wr, int wc, int fr, int fq) const {
;     ...
;             for (int m = 0; m < 4; ++m) { const float rs = row_rstd(ssq, row0 + ai * 128 + m * 16, fq); float mx = -3.0e38f;
; #pragma unroll
;                 for (int bj = 0; bj < 2; ++bj)
; #pragma unroll
;                     for (int n = 0; n < 2; ++n) { const f32x4 a = acc[ai][bj][m][n]; mx = fmaxf(mx, fmaxf(fmaxf(a[0], a[1]), fmaxf(a[2], a[3]))); }
;                 mx *= rs; mx = fmaxf(mx, __shfl_xor(mx, 16)); mx = fmaxf(mx, __shfl_xor(mx, 32));
;                 if (fq == 0) xch[(lrow0 + ai * 128 + m * 16) * 4 + wc] = mx; }
;         asm volatile("s_waitcnt lgkmcnt(0)" ::: "memory"); __builtin_amdgcn_s_barrier(); asm volatile("" ::: "memory");
; #pragma unroll
;         for (int ai = 0; ai < 2; ++ai)
; #pragma unroll
;             for (int m = 0; m < 4; ++m) { const f32x4 x4 = *(const LAS f32x4*)(xch + (lrow0 + ai * 128 + m * 16) * 4); const float mrow = fmaxf(fmaxf(x4[0], x4[1]), fmaxf(x4[2], x4[3])), rs = row_rstd(ssq, row0 + ai * 128 + m * 16, fq); float sm = 0.f;
; #pragma unroll
;                 for (int bj = 0; bj < 2; ++bj)
; #pragma unroll
;                     for (int n = 0; n < 2; ++n) { f32x4 a = acc[ai][bj][m][n];
; #pragma unroll
;                         for (int i = 0; i < 4; ++i) { a[i] = __expf(a[i] * rs - mrow); sm += a[i]; }
;                         asm volatile("" ::: "memory");
;                         acc[ai][bj][m][n] = a; }
;                 sm += __shfl_xor(sm, 16); sm += __shfl_xor(sm, 32);
;                 if (fq == 0) xch[1024 + (lrow0 + ai * 128 + m * 16) * 4 + wc] = sm; }
.LBB0_1008:
	s_or_b64 exec, exec, s[24:25]
	v_add_u32_e32 v152, 0x90, v142
	s_waitcnt lgkmcnt(0)
	v_ashrrev_i32_e32 v153, 31, v152
	v_lshlrev_b64 v[154:155], 6, v[152:153]
	v_lshl_add_u64 v[168:169], v[136:137], 0, v[154:155]
	s_nop 0
	v_max_f32_e32 v170, v34, v34
	s_waitcnt lgkmcnt(0)
	s_nop 0
	s_nop 0
	s_nop 0
	s_nop 0
	v_max_f32_e32 v156, v46, v46
	v_max_f32_e32 v157, v42, v42
	s_waitcnt lgkmcnt(0)
	s_nop 0
	s_nop 0
	s_waitcnt lgkmcnt(0)
	s_nop 0
	v_max_f32_e32 v155, v47, v47
	v_max_f32_e32 v155, v156, v155
	v_max_f32_e32 v156, v43, v43
	v_max_f32_e32 v156, v157, v156
	v_max3_f32 v155, v44, v45, v155
	v_max3_f32 v156, v40, v41, v156
	s_nop 0
	v_max3_f32 v155, v155, s2, v156
	v_max_f32_e32 v156, v39, v39
	v_max_f32_e32 v157, v38, v38
	v_max_f32_e32 v156, v157, v156
	v_max_f32_e32 v157, v35, v35
	v_mov_b32_e32 v154, v251
	v_max_f32_e32 v157, v170, v157
	v_max3_f32 v156, v36, v37, v156
	v_max3_f32 v157, v32, v33, v157
	v_max3_f32 v155, v155, v156, v157
	v_mul_f32_e32 v154, v155, v154
	ds_bpermute_b32 v155, v209, v154
	s_waitcnt lgkmcnt(0)
	v_max_f32_e32 v155, v155, v155
	v_max_f32_e32 v154, v154, v155
	ds_bpermute_b32 v155, v208, v154
	s_and_saveexec_b64 s[24:25], s[4:5]
	s_cbranch_execz .LBB0_1010
	s_waitcnt lgkmcnt(0)
	v_max_f32_e32 v155, v155, v155
	v_max_f32_e32 v154, v154, v154
	v_max_f32_e32 v154, v154, v155
	ds_write_b32 v210, v154 offset:2304
.LBB0_1010:
	s_or_b64 exec, exec, s[24:25]
	v_add_u32_e32 v154, 0xa0, v142
	s_waitcnt lgkmcnt(0)
	v_ashrrev_i32_e32 v155, 31, v154
	v_lshlrev_b64 v[156:157], 6, v[154:155]
	v_lshl_add_u64 v[170:171], v[136:137], 0, v[156:157]
	s_nop 0
	v_max_f32_e32 v172, v30, v30
	v_max_f32_e32 v173, v26, v26
	v_max_f32_e32 v194, v18, v18
	s_waitcnt lgkmcnt(0)
	s_nop 0
	s_nop 0
	s_nop 0
	s_nop 0
	s_waitcnt lgkmcnt(0)
	s_nop 0
	s_nop 0
	s_waitcnt lgkmcnt(0)
	s_nop 0
	v_max_f32_e32 v157, v31, v31
	v_max_f32_e32 v157, v172, v157
	v_max_f32_e32 v172, v27, v27
	v_max_f32_e32 v172, v173, v172
	v_max3_f32 v157, v28, v29, v157
	v_max3_f32 v172, v24, v25, v172
	s_nop 0
	v_max3_f32 v157, v157, s2, v172
	v_max_f32_e32 v172, v23, v23
	v_max_f32_e32 v173, v22, v22
	v_max_f32_e32 v172, v173, v172
	v_max_f32_e32 v173, v19, v19
	v_mov_b32_e32 v156, v252
	v_max_f32_e32 v173, v194, v173
	v_max3_f32 v172, v20, v21, v172
	v_max3_f32 v173, v16, v17, v173
	v_max3_f32 v157, v157, v172, v173
	v_mul_f32_e32 v156, v157, v156
	ds_bpermute_b32 v157, v209, v156
	s_waitcnt lgkmcnt(0)
	v_max_f32_e32 v157, v157, v157
	v_max_f32_e32 v156, v156, v157
	ds_bpermute_b32 v157, v208, v156
	s_and_saveexec_b64 s[24:25], s[4:5]
	s_cbranch_execz .LBB0_1012
	s_waitcnt lgkmcnt(0)
	v_max_f32_e32 v157, v157, v157
	v_max_f32_e32 v156, v156, v156
	v_max_f32_e32 v156, v156, v157
	ds_write_b32 v210, v156 offset:2560
.LBB0_1012:
	s_or_b64 exec, exec, s[24:25]
	v_add_u32_e32 v156, 0xb0, v142
	s_waitcnt lgkmcnt(0)
	v_ashrrev_i32_e32 v157, 31, v156
	v_lshlrev_b64 v[172:173], 6, v[156:157]
	v_lshl_add_u64 v[172:173], v[136:137], 0, v[172:173]
	s_nop 0
	v_max_f32_e32 v211, v14, v14
	s_waitcnt lgkmcnt(0)
	s_nop 0
	s_nop 0
	s_nop 0
	s_nop 0
	v_max_f32_e32 v218, v10, v10
	v_max_f32_e32 v219, v2, v2
	s_waitcnt lgkmcnt(0)
	s_nop 0
	s_nop 0
	s_waitcnt lgkmcnt(0)
	s_nop 0
	v_max_f32_e32 v195, v15, v15
	v_max_f32_e32 v195, v211, v195
	v_max_f32_e32 v211, v11, v11
	v_max_f32_e32 v211, v218, v211
	v_max3_f32 v195, v12, v13, v195
	v_max3_f32 v211, v8, v9, v211
	s_nop 0
	v_max3_f32 v195, v195, s2, v211
	v_max_f32_e32 v211, v7, v7
	v_max_f32_e32 v218, v6, v6
	v_max_f32_e32 v211, v218, v211
	v_max_f32_e32 v218, v3, v3
	v_mov_b32_e32 v194, v253
	v_max_f32_e32 v218, v219, v218
	v_max3_f32 v211, v4, v5, v211
	v_max3_f32 v218, v0, v1, v218
	v_max3_f32 v195, v195, v211, v218
	v_mul_f32_e32 v194, v195, v194
	ds_bpermute_b32 v195, v209, v194
	s_waitcnt lgkmcnt(0)
	v_max_f32_e32 v195, v195, v195
	v_max_f32_e32 v211, v194, v195
	ds_bpermute_b32 v218, v208, v211
	s_and_saveexec_b64 s[24:25], s[4:5]
	s_cbranch_execz .LBB0_1014
	s_waitcnt lgkmcnt(0)
	v_max_f32_e32 v194, v218, v218
	v_max_f32_e32 v195, v211, v211
	v_max_f32_e32 v194, v195, v194
	ds_write_b32 v210, v194 offset:2816
.LBB0_1014:
	s_or_b64 exec, exec, s[24:25]
	s_waitcnt lgkmcnt(0)
	s_barrier
	s_waitcnt lgkmcnt(0)
	s_nop 0
	s_waitcnt lgkmcnt(0)
	s_nop 0
	s_nop 0
	s_nop 0
	s_nop 0
	ds_read_b128 v[218:221], v180
	s_nop 0
	s_nop 0
	s_waitcnt lgkmcnt(0)
	v_max_f32_e32 v194, v221, v221
	s_waitcnt lgkmcnt(0)
	s_nop 0
	s_nop 0
	s_waitcnt lgkmcnt(0)
	s_nop 0
	s_nop 0
	v_mov_b32_e32 v158, v246
	v_max_f32_e32 v159, v220, v220
	v_max_f32_e32 v159, v159, v194
	v_max3_f32 v159, v218, v219, v159
	v_fma_f32 v124, v124, v158, -v159
	v_fma_f32 v125, v125, v158, -v159
	v_fma_f32 v122, v122, v158, -v159
	v_mul_f32_e32 v124, 0x3fb8aa3b, v124
	v_fma_f32 v126, v126, v158, -v159
	v_fma_f32 v127, v127, v158, -v159
	v_fma_f32 v120, v120, v158, -v159
	v_fma_f32 v121, v121, v158, -v159
	v_fma_f32 v123, v123, v158, -v159
	v_fma_f32 v116, v116, v158, -v159
	v_fma_f32 v117, v117, v158, -v159
	v_fma_f32 v118, v118, v158, -v159
	v_fma_f32 v119, v119, v158, -v159
	v_fma_f32 v112, v112, v158, -v159
	v_fma_f32 v113, v113, v158, -v159
	v_fma_f32 v114, v114, v158, -v159
	v_fma_f32 v115, v115, v158, -v159
	v_mul_f32_e32 v125, 0x3fb8aa3b, v125
	v_mul_f32_e32 v158, 0x3fb8aa3b, v122
	v_exp_f32_e32 v122, v124
	v_mul_f32_e32 v126, 0x3fb8aa3b, v126
	v_mul_f32_e32 v159, 0x3fb8aa3b, v123
	v_exp_f32_e32 v123, v125
	v_mul_f32_e32 v127, 0x3fb8aa3b, v127
	v_exp_f32_e32 v126, v126
	v_mul_f32_e32 v120, 0x3fb8aa3b, v120
	v_mul_f32_e32 v117, 0x3fb8aa3b, v117
	v_exp_f32_e32 v127, v127
	v_mul_f32_e32 v121, 0x3fb8aa3b, v121
	v_mul_f32_e32 v195, 0x3fb8aa3b, v115
	v_exp_f32_e32 v120, v120
	v_exp_f32_e32 v115, v117
	v_add_f32_e32 v117, 0, v122
	v_exp_f32_e32 v121, v121
	v_add_f32_e32 v117, v123, v117
	v_exp_f32_e32 v124, v158
	v_add_f32_e32 v117, v126, v117
	v_mul_f32_e32 v116, 0x3fb8aa3b, v116
	v_exp_f32_e32 v125, v159
	v_add_f32_e32 v117, v127, v117
	v_mul_f32_e32 v194, 0x3fb8aa3b, v114
	v_exp_f32_e32 v114, v116
	v_add_f32_e32 v117, v120, v117
	v_mul_f32_e32 v118, 0x3fb8aa3b, v118
	v_add_f32_e32 v117, v121, v117
	v_mul_f32_e32 v119, 0x3fb8aa3b, v119
	v_exp_f32_e32 v118, v118
	v_add_f32_e32 v117, v124, v117
	v_mul_f32_e32 v112, 0x3fb8aa3b, v112
	v_exp_f32_e32 v119, v119
	v_add_f32_e32 v117, v125, v117
	v_mul_f32_e32 v113, 0x3fb8aa3b, v113
	v_exp_f32_e32 v112, v112
	v_add_f32_e32 v117, v114, v117
	v_exp_f32_e32 v113, v113
	v_add_f32_e32 v117, v115, v117
	v_exp_f32_e32 v116, v194
	v_add_f32_e32 v117, v118, v117
	v_add_f32_e32 v158, v119, v117
	v_exp_f32_e32 v117, v195
	v_add_f32_e32 v158, v112, v158
	v_add_f32_e32 v158, v113, v158
	v_add_f32_e32 v158, v116, v158
	v_add_f32_e32 v158, v117, v158
	ds_bpermute_b32 v159, v209, v158
	s_waitcnt lgkmcnt(0)
	v_add_f32_e32 v158, v158, v159
	ds_bpermute_b32 v159, v208, v158
	s_and_saveexec_b64 s[24:25], s[4:5]
	s_cbranch_execz .LBB0_1016
	s_waitcnt lgkmcnt(0)
	v_add_f32_e32 v158, v158, v159
	ds_write_b32 v181, v158 offset:4096
; #define LAS __attribute__((address_space(3)))
;     __device__ __forceinline__ void operator()(const f32x4 (&acc_)[2][2][4][2], const pg8::Unit& u, int wr, int wc, int fr, int fq) const {
;     ...
;             for (int m = 0; m < 4; ++m) { const f32x4 x4 = *(const LAS f32x4*)(xch + (lrow0 + ai * 128 + m * 16) * 4); const float mrow = fmaxf(fmaxf(x4[0], x4[1]), fmaxf(x4[2], x4[3])), rs = row_rstd(ssq, row0 + ai * 128 + m * 16, fq); float sm = 0.f;
; #pragma unroll
;                 for (int bj = 0; bj < 2; ++bj)
; #pragma unroll
;                     for (int n = 0; n < 2; ++n) { f32x4 a = acc[ai][bj][m][n];
; #pragma unroll
;                         for (int i = 0; i < 4; ++i) { a[i] = __expf(a[i] * rs - mrow); sm += a[i]; }
;                         asm volatile("" ::: "memory");
;                         acc[ai][bj][m][n] = a; }
;                 sm += __shfl_xor(sm, 16); sm += __shfl_xor(sm, 32);
;                 if (fq == 0) xch[1024 + (lrow0 + ai * 128 + m * 16) * 4 + wc] = sm; }
.LBB0_1016:
	s_or_b64 exec, exec, s[24:25]
	s_waitcnt lgkmcnt(0)
	s_nop 0
	s_waitcnt lgkmcnt(0)
	s_nop 0
	s_nop 0
	s_nop 0
	s_nop 0
	s_nop 0
	s_nop 0
	s_nop 0
	ds_read_b128 v[158:161], v182
	s_waitcnt lgkmcnt(0)
	s_nop 0
	s_nop 0
	s_waitcnt lgkmcnt(0)
	v_max_f32_e32 v161, v161, v161
	v_max_f32_e32 v160, v160, v160
	v_max_f32_e32 v160, v160, v161
	v_max3_f32 v158, v158, v159, v160
	s_waitcnt lgkmcnt(0)
	s_nop 0
	s_nop 0
	v_mov_b32_e32 v194, v247
	s_nop 0
	v_fma_f32 v108, v108, v194, -v158
	v_fma_f32 v109, v109, v194, -v158
	v_fma_f32 v106, v106, v194, -v158
	v_mul_f32_e32 v108, 0x3fb8aa3b, v108
	v_fma_f32 v110, v110, v194, -v158
	v_fma_f32 v111, v111, v194, -v158
	v_fma_f32 v104, v104, v194, -v158
	v_fma_f32 v105, v105, v194, -v158
	v_fma_f32 v107, v107, v194, -v158
	v_fma_f32 v100, v100, v194, -v158
	v_fma_f32 v101, v101, v194, -v158
	v_fma_f32 v102, v102, v194, -v158
	v_fma_f32 v103, v103, v194, -v158
	v_fma_f32 v96, v96, v194, -v158
	v_fma_f32 v97, v97, v194, -v158
	v_fma_f32 v98, v98, v194, -v158
	v_fma_f32 v99, v99, v194, -v158
	v_mul_f32_e32 v109, 0x3fb8aa3b, v109
	v_mul_f32_e32 v158, 0x3fb8aa3b, v106
	v_exp_f32_e32 v106, v108
	v_mul_f32_e32 v110, 0x3fb8aa3b, v110
	v_mul_f32_e32 v159, 0x3fb8aa3b, v107
	v_exp_f32_e32 v107, v109
	v_mul_f32_e32 v111, 0x3fb8aa3b, v111
	v_exp_f32_e32 v110, v110
	v_mul_f32_e32 v104, 0x3fb8aa3b, v104
	v_mul_f32_e32 v101, 0x3fb8aa3b, v101
	v_exp_f32_e32 v111, v111
	v_mul_f32_e32 v105, 0x3fb8aa3b, v105
	v_mul_f32_e32 v161, 0x3fb8aa3b, v99
	v_exp_f32_e32 v104, v104
	v_exp_f32_e32 v99, v101
	v_add_f32_e32 v101, 0, v106
	v_exp_f32_e32 v105, v105
	v_add_f32_e32 v101, v107, v101
	v_exp_f32_e32 v108, v158
	v_add_f32_e32 v101, v110, v101
	v_mul_f32_e32 v100, 0x3fb8aa3b, v100
	v_exp_f32_e32 v109, v159
	v_add_f32_e32 v101, v111, v101
	v_mul_f32_e32 v160, 0x3fb8aa3b, v98
	v_exp_f32_e32 v98, v100
	v_add_f32_e32 v101, v104, v101
	v_mul_f32_e32 v102, 0x3fb8aa3b, v102
	v_add_f32_e32 v101, v105, v101
	v_mul_f32_e32 v103, 0x3fb8aa3b, v103
	v_exp_f32_e32 v102, v102
	v_add_f32_e32 v101, v108, v101
	v_mul_f32_e32 v96, 0x3fb8aa3b, v96
	v_exp_f32_e32 v103, v103
	v_add_f32_e32 v101, v109, v101
	v_mul_f32_e32 v97, 0x3fb8aa3b, v97
	v_exp_f32_e32 v96, v96
	v_add_f32_e32 v101, v98, v101
	v_exp_f32_e32 v97, v97
	v_add_f32_e32 v101, v99, v101
	v_exp_f32_e32 v100, v160
	v_add_f32_e32 v101, v102, v101
	v_add_f32_e32 v158, v103, v101
	v_exp_f32_e32 v101, v161
	v_add_f32_e32 v158, v96, v158
	v_add_f32_e32 v158, v97, v158
	v_add_f32_e32 v158, v100, v158
	v_add_f32_e32 v158, v101, v158
	ds_bpermute_b32 v159, v209, v158
	s_waitcnt lgkmcnt(0)
	v_add_f32_e32 v158, v158, v159
	ds_bpermute_b32 v159, v208, v158
	s_and_saveexec_b64 s[24:25], s[4:5]
	s_cbranch_execz .LBB0_1018
	s_waitcnt lgkmcnt(0)
	v_add_f32_e32 v158, v158, v159
	ds_write_b32 v183, v158 offset:4096
.LBB0_1018:
	s_or_b64 exec, exec, s[24:25]
	s_waitcnt lgkmcnt(0)
	s_nop 0
	s_waitcnt lgkmcnt(0)
	s_nop 0
	s_nop 0
	s_nop 0
	s_nop 0
	s_nop 0
	s_nop 0
	s_nop 0
	ds_read_b128 v[158:161], v184
	s_waitcnt lgkmcnt(0)
	s_nop 0
	s_nop 0
	s_waitcnt lgkmcnt(0)
	v_max_f32_e32 v161, v161, v161
	v_max_f32_e32 v160, v160, v160
	v_max_f32_e32 v160, v160, v161
	v_max3_f32 v158, v158, v159, v160
	s_waitcnt lgkmcnt(0)
	s_nop 0
	s_nop 0
	v_mov_b32_e32 v162, v248
	s_nop 0
	v_fma_f32 v92, v92, v162, -v158
	v_fma_f32 v93, v93, v162, -v158
	v_fma_f32 v90, v90, v162, -v158
	v_mul_f32_e32 v92, 0x3fb8aa3b, v92
	v_fma_f32 v94, v94, v162, -v158
	v_fma_f32 v95, v95, v162, -v158
	v_fma_f32 v88, v88, v162, -v158
	v_fma_f32 v89, v89, v162, -v158
	v_fma_f32 v91, v91, v162, -v158
	v_fma_f32 v84, v84, v162, -v158
	v_fma_f32 v85, v85, v162, -v158
	v_fma_f32 v86, v86, v162, -v158
	v_fma_f32 v87, v87, v162, -v158
	v_fma_f32 v80, v80, v162, -v158
	v_fma_f32 v81, v81, v162, -v158
	v_fma_f32 v82, v82, v162, -v158
	v_fma_f32 v83, v83, v162, -v158
	v_mul_f32_e32 v93, 0x3fb8aa3b, v93
	v_mul_f32_e32 v158, 0x3fb8aa3b, v90
	v_exp_f32_e32 v90, v92
	v_mul_f32_e32 v94, 0x3fb8aa3b, v94
	v_mul_f32_e32 v159, 0x3fb8aa3b, v91
	v_exp_f32_e32 v91, v93
	v_mul_f32_e32 v95, 0x3fb8aa3b, v95
	v_exp_f32_e32 v94, v94
	v_mul_f32_e32 v88, 0x3fb8aa3b, v88
	v_mul_f32_e32 v85, 0x3fb8aa3b, v85
	v_exp_f32_e32 v95, v95
	v_mul_f32_e32 v89, 0x3fb8aa3b, v89
	v_mul_f32_e32 v161, 0x3fb8aa3b, v83
	v_exp_f32_e32 v88, v88
	v_exp_f32_e32 v83, v85
	v_add_f32_e32 v85, 0, v90
	v_exp_f32_e32 v89, v89
	v_add_f32_e32 v85, v91, v85
	v_exp_f32_e32 v92, v158
	v_add_f32_e32 v85, v94, v85
	v_mul_f32_e32 v84, 0x3fb8aa3b, v84
	v_exp_f32_e32 v93, v159
	v_add_f32_e32 v85, v95, v85
	v_mul_f32_e32 v160, 0x3fb8aa3b, v82
	v_exp_f32_e32 v82, v84
	v_add_f32_e32 v85, v88, v85
	v_mul_f32_e32 v86, 0x3fb8aa3b, v86
	v_add_f32_e32 v85, v89, v85
	v_mul_f32_e32 v87, 0x3fb8aa3b, v87
	v_exp_f32_e32 v86, v86
	v_add_f32_e32 v85, v92, v85
	v_mul_f32_e32 v80, 0x3fb8aa3b, v80
	v_exp_f32_e32 v87, v87
	v_add_f32_e32 v85, v93, v85
	v_mul_f32_e32 v81, 0x3fb8aa3b, v81
	v_exp_f32_e32 v80, v80
	v_add_f32_e32 v85, v82, v85
	v_exp_f32_e32 v81, v81
	v_add_f32_e32 v85, v83, v85
	v_exp_f32_e32 v84, v160
	v_add_f32_e32 v85, v86, v85
	v_add_f32_e32 v158, v87, v85
	v_exp_f32_e32 v85, v161
	v_add_f32_e32 v158, v80, v158
	v_add_f32_e32 v158, v81, v158
	v_add_f32_e32 v158, v84, v158
	v_add_f32_e32 v158, v85, v158
	ds_bpermute_b32 v159, v209, v158
	s_waitcnt lgkmcnt(0)
	v_add_f32_e32 v158, v158, v159
	ds_bpermute_b32 v159, v208, v158
	s_and_saveexec_b64 s[24:25], s[4:5]
	s_cbranch_execz .LBB0_1020
	s_waitcnt lgkmcnt(0)
	v_add_f32_e32 v158, v158, v159
	ds_write_b32 v185, v158 offset:4096
; #define LAS __attribute__((address_space(3)))
;     __device__ __forceinline__ void operator()(const f32x4 (&acc_)[2][2][4][2], const pg8::Unit& u, int wr, int wc, int fr, int fq) const {
;     ...
;             for (int m = 0; m < 4; ++m) { const f32x4 x4 = *(const LAS f32x4*)(xch + (lrow0 + ai * 128 + m * 16) * 4); const float mrow = fmaxf(fmaxf(x4[0], x4[1]), fmaxf(x4[2], x4[3])), rs = row_rstd(ssq, row0 + ai * 128 + m * 16, fq); float sm = 0.f;
; #pragma unroll
;                 for (int bj = 0; bj < 2; ++bj)
; #pragma unroll
;                     for (int n = 0; n < 2; ++n) { f32x4 a = acc[ai][bj][m][n];
; #pragma unroll
;                         for (int i = 0; i < 4; ++i) { a[i] = __expf(a[i] * rs - mrow); sm += a[i]; }
;                         asm volatile("" ::: "memory");
;                         acc[ai][bj][m][n] = a; }
;                 sm += __shfl_xor(sm, 16); sm += __shfl_xor(sm, 32);
;                 if (fq == 0) xch[1024 + (lrow0 + ai * 128 + m * 16) * 4 + wc] = sm; }
.LBB0_1020:
	s_or_b64 exec, exec, s[24:25]
	s_waitcnt lgkmcnt(0)
	s_nop 0
	s_waitcnt lgkmcnt(0)
	s_nop 0
	s_nop 0
	s_nop 0
	s_nop 0
	s_nop 0
	s_nop 0
	s_nop 0
	ds_read_b128 v[158:161], v186
	s_waitcnt lgkmcnt(0)
	s_nop 0
	s_nop 0
	s_waitcnt lgkmcnt(0)
	v_max_f32_e32 v161, v161, v161
	v_max_f32_e32 v160, v160, v160
	v_max_f32_e32 v160, v160, v161
	v_max3_f32 v158, v158, v159, v160
	s_waitcnt lgkmcnt(0)
	s_nop 0
	s_nop 0
	v_mov_b32_e32 v162, v249
	s_nop 0
	v_fma_f32 v76, v76, v162, -v158
	v_fma_f32 v77, v77, v162, -v158
	v_fma_f32 v74, v74, v162, -v158
	v_mul_f32_e32 v76, 0x3fb8aa3b, v76
	v_fma_f32 v78, v78, v162, -v158
	v_fma_f32 v79, v79, v162, -v158
	v_fma_f32 v72, v72, v162, -v158
	v_fma_f32 v73, v73, v162, -v158
	v_fma_f32 v75, v75, v162, -v158
	v_fma_f32 v68, v68, v162, -v158
	v_fma_f32 v69, v69, v162, -v158
	v_fma_f32 v70, v70, v162, -v158
	v_fma_f32 v71, v71, v162, -v158
	v_fma_f32 v64, v64, v162, -v158
	v_fma_f32 v65, v65, v162, -v158
	v_fma_f32 v66, v66, v162, -v158
	v_fma_f32 v67, v67, v162, -v158
	v_mul_f32_e32 v77, 0x3fb8aa3b, v77
	v_mul_f32_e32 v158, 0x3fb8aa3b, v74
	v_exp_f32_e32 v74, v76
	v_mul_f32_e32 v78, 0x3fb8aa3b, v78
	v_mul_f32_e32 v159, 0x3fb8aa3b, v75
	v_exp_f32_e32 v75, v77
	v_mul_f32_e32 v79, 0x3fb8aa3b, v79
	v_exp_f32_e32 v78, v78
	v_mul_f32_e32 v72, 0x3fb8aa3b, v72
	v_mul_f32_e32 v69, 0x3fb8aa3b, v69
	v_exp_f32_e32 v79, v79
	v_mul_f32_e32 v73, 0x3fb8aa3b, v73
	v_mul_f32_e32 v161, 0x3fb8aa3b, v67
	v_exp_f32_e32 v72, v72
	v_exp_f32_e32 v67, v69
	v_add_f32_e32 v69, 0, v74
	v_exp_f32_e32 v73, v73
	v_add_f32_e32 v69, v75, v69
	v_exp_f32_e32 v76, v158
	v_add_f32_e32 v69, v78, v69
	v_mul_f32_e32 v68, 0x3fb8aa3b, v68
	v_exp_f32_e32 v77, v159
	v_add_f32_e32 v69, v79, v69
	v_mul_f32_e32 v160, 0x3fb8aa3b, v66
	v_exp_f32_e32 v66, v68
	v_add_f32_e32 v69, v72, v69
	v_mul_f32_e32 v70, 0x3fb8aa3b, v70
	v_add_f32_e32 v69, v73, v69
	v_mul_f32_e32 v71, 0x3fb8aa3b, v71
	v_exp_f32_e32 v70, v70
	v_add_f32_e32 v69, v76, v69
	v_mul_f32_e32 v64, 0x3fb8aa3b, v64
	v_exp_f32_e32 v71, v71
	v_add_f32_e32 v69, v77, v69
	v_mul_f32_e32 v65, 0x3fb8aa3b, v65
	v_exp_f32_e32 v64, v64
	v_add_f32_e32 v69, v66, v69
	v_exp_f32_e32 v65, v65
	v_add_f32_e32 v69, v67, v69
	v_exp_f32_e32 v68, v160
	v_add_f32_e32 v69, v70, v69
	v_add_f32_e32 v158, v71, v69
	v_exp_f32_e32 v69, v161
	v_add_f32_e32 v158, v64, v158
	v_add_f32_e32 v158, v65, v158
	v_add_f32_e32 v158, v68, v158
	v_add_f32_e32 v158, v69, v158
	ds_bpermute_b32 v159, v209, v158
	s_waitcnt lgkmcnt(0)
	v_add_f32_e32 v158, v158, v159
	ds_bpermute_b32 v159, v208, v158
	s_and_saveexec_b64 s[24:25], s[4:5]
	s_cbranch_execz .LBB0_1022
	s_waitcnt lgkmcnt(0)
	v_add_f32_e32 v158, v158, v159
	ds_write_b32 v187, v158 offset:4096
.LBB0_1022:
	s_or_b64 exec, exec, s[24:25]
	s_waitcnt lgkmcnt(0)
	s_nop 0
	s_waitcnt lgkmcnt(0)
	s_nop 0
	s_nop 0
	s_nop 0
	s_nop 0
	s_nop 0
	s_nop 0
	s_nop 0
	ds_read_b128 v[158:161], v188
	s_waitcnt lgkmcnt(0)
	s_nop 0
	s_nop 0
	s_waitcnt lgkmcnt(0)
	v_max_f32_e32 v161, v161, v161
	v_max_f32_e32 v160, v160, v160
	v_max_f32_e32 v160, v160, v161
	v_max3_f32 v158, v158, v159, v160
	s_waitcnt lgkmcnt(0)
	s_nop 0
	s_nop 0
	v_mov_b32_e32 v162, v250
	s_nop 0
	v_fma_f32 v60, v60, v162, -v158
	v_fma_f32 v61, v61, v162, -v158
	v_fma_f32 v58, v58, v162, -v158
	v_mul_f32_e32 v60, 0x3fb8aa3b, v60
	v_fma_f32 v62, v62, v162, -v158
	v_fma_f32 v63, v63, v162, -v158
	v_fma_f32 v56, v56, v162, -v158
	v_fma_f32 v57, v57, v162, -v158
	v_fma_f32 v59, v59, v162, -v158
	v_fma_f32 v52, v52, v162, -v158
	v_fma_f32 v53, v53, v162, -v158
	v_fma_f32 v54, v54, v162, -v158
	v_fma_f32 v55, v55, v162, -v158
	v_fma_f32 v48, v48, v162, -v158
	v_fma_f32 v49, v49, v162, -v158
	v_fma_f32 v50, v50, v162, -v158
	v_fma_f32 v51, v51, v162, -v158
	v_mul_f32_e32 v61, 0x3fb8aa3b, v61
	v_mul_f32_e32 v158, 0x3fb8aa3b, v58
	v_exp_f32_e32 v58, v60
	v_mul_f32_e32 v62, 0x3fb8aa3b, v62
	v_mul_f32_e32 v159, 0x3fb8aa3b, v59
	v_exp_f32_e32 v59, v61
	v_mul_f32_e32 v63, 0x3fb8aa3b, v63
	v_exp_f32_e32 v62, v62
	v_mul_f32_e32 v56, 0x3fb8aa3b, v56
	v_mul_f32_e32 v53, 0x3fb8aa3b, v53
	v_exp_f32_e32 v63, v63
	v_mul_f32_e32 v57, 0x3fb8aa3b, v57
	v_mul_f32_e32 v161, 0x3fb8aa3b, v51
	v_exp_f32_e32 v56, v56
	v_exp_f32_e32 v51, v53
	v_add_f32_e32 v53, 0, v58
	v_exp_f32_e32 v57, v57
	v_add_f32_e32 v53, v59, v53
	v_exp_f32_e32 v60, v158
	v_add_f32_e32 v53, v62, v53
	v_mul_f32_e32 v52, 0x3fb8aa3b, v52
	v_exp_f32_e32 v61, v159
	v_add_f32_e32 v53, v63, v53
	v_mul_f32_e32 v160, 0x3fb8aa3b, v50
	v_exp_f32_e32 v50, v52
	v_add_f32_e32 v53, v56, v53
	v_mul_f32_e32 v54, 0x3fb8aa3b, v54
	v_add_f32_e32 v53, v57, v53
	v_mul_f32_e32 v55, 0x3fb8aa3b, v55
	v_exp_f32_e32 v54, v54
	v_add_f32_e32 v53, v60, v53
	v_mul_f32_e32 v48, 0x3fb8aa3b, v48
	v_exp_f32_e32 v55, v55
	v_add_f32_e32 v53, v61, v53
	v_mul_f32_e32 v49, 0x3fb8aa3b, v49
	v_exp_f32_e32 v48, v48
	v_add_f32_e32 v53, v50, v53
	v_exp_f32_e32 v49, v49
	v_add_f32_e32 v53, v51, v53
	v_exp_f32_e32 v52, v160
	v_add_f32_e32 v53, v54, v53
	v_add_f32_e32 v158, v55, v53
	v_exp_f32_e32 v53, v161
	v_add_f32_e32 v158, v48, v158
	v_add_f32_e32 v158, v49, v158
	v_add_f32_e32 v158, v52, v158
	v_add_f32_e32 v158, v53, v158
	ds_bpermute_b32 v159, v209, v158
	s_waitcnt lgkmcnt(0)
	v_add_f32_e32 v158, v158, v159
	ds_bpermute_b32 v159, v208, v158
	s_and_saveexec_b64 s[24:25], s[4:5]
	s_cbranch_execz .LBB0_1024
	s_waitcnt lgkmcnt(0)
	v_add_f32_e32 v158, v158, v159
	ds_write_b32 v189, v158 offset:4096
; #define LAS __attribute__((address_space(3)))
;     __device__ __forceinline__ void operator()(const f32x4 (&acc_)[2][2][4][2], const pg8::Unit& u, int wr, int wc, int fr, int fq) const {
;     ...
;             for (int m = 0; m < 4; ++m) { const f32x4 x4 = *(const LAS f32x4*)(xch + (lrow0 + ai * 128 + m * 16) * 4); const float mrow = fmaxf(fmaxf(x4[0], x4[1]), fmaxf(x4[2], x4[3])), rs = row_rstd(ssq, row0 + ai * 128 + m * 16, fq); float sm = 0.f;
; #pragma unroll
;                 for (int bj = 0; bj < 2; ++bj)
; #pragma unroll
;                     for (int n = 0; n < 2; ++n) { f32x4 a = acc[ai][bj][m][n];
; #pragma unroll
;                         for (int i = 0; i < 4; ++i) { a[i] = __expf(a[i] * rs - mrow); sm += a[i]; }
;                         asm volatile("" ::: "memory");
;                         acc[ai][bj][m][n] = a; }
;                 sm += __shfl_xor(sm, 16); sm += __shfl_xor(sm, 32);
;                 if (fq == 0) xch[1024 + (lrow0 + ai * 128 + m * 16) * 4 + wc] = sm; }
.LBB0_1024:
	s_or_b64 exec, exec, s[24:25]
	s_waitcnt lgkmcnt(0)
	s_nop 0
	s_waitcnt lgkmcnt(0)
	s_nop 0
	s_nop 0
	s_nop 0
	s_nop 0
	s_nop 0
	s_nop 0
	s_nop 0
	ds_read_b128 v[158:161], v190
	s_waitcnt lgkmcnt(0)
	s_nop 0
	s_nop 0
	s_waitcnt lgkmcnt(0)
	v_max_f32_e32 v161, v161, v161
	v_max_f32_e32 v160, v160, v160
	v_max_f32_e32 v160, v160, v161
	v_max3_f32 v158, v158, v159, v160
	s_waitcnt lgkmcnt(0)
	s_nop 0
	s_nop 0
	v_mov_b32_e32 v162, v251
	s_nop 0
	v_fma_f32 v44, v44, v162, -v158
	v_fma_f32 v45, v45, v162, -v158
	v_fma_f32 v42, v42, v162, -v158
	v_mul_f32_e32 v44, 0x3fb8aa3b, v44
	v_fma_f32 v46, v46, v162, -v158
	v_fma_f32 v47, v47, v162, -v158
	v_fma_f32 v40, v40, v162, -v158
	v_fma_f32 v41, v41, v162, -v158
	v_fma_f32 v43, v43, v162, -v158
	v_fma_f32 v36, v36, v162, -v158
	v_fma_f32 v37, v37, v162, -v158
	v_fma_f32 v38, v38, v162, -v158
	v_fma_f32 v39, v39, v162, -v158
	v_fma_f32 v32, v32, v162, -v158
	v_fma_f32 v33, v33, v162, -v158
	v_fma_f32 v34, v34, v162, -v158
	v_fma_f32 v35, v35, v162, -v158
	v_mul_f32_e32 v45, 0x3fb8aa3b, v45
	v_mul_f32_e32 v158, 0x3fb8aa3b, v42
	v_exp_f32_e32 v42, v44
	v_mul_f32_e32 v46, 0x3fb8aa3b, v46
	v_mul_f32_e32 v159, 0x3fb8aa3b, v43
	v_exp_f32_e32 v43, v45
	v_mul_f32_e32 v47, 0x3fb8aa3b, v47
	v_exp_f32_e32 v46, v46
	v_mul_f32_e32 v40, 0x3fb8aa3b, v40
	v_mul_f32_e32 v37, 0x3fb8aa3b, v37
	v_exp_f32_e32 v47, v47
	v_mul_f32_e32 v41, 0x3fb8aa3b, v41
	v_mul_f32_e32 v161, 0x3fb8aa3b, v35
	v_exp_f32_e32 v40, v40
	v_exp_f32_e32 v35, v37
	v_add_f32_e32 v37, 0, v42
	v_exp_f32_e32 v41, v41
	v_add_f32_e32 v37, v43, v37
	v_exp_f32_e32 v44, v158
	v_add_f32_e32 v37, v46, v37
	v_mul_f32_e32 v36, 0x3fb8aa3b, v36
	v_exp_f32_e32 v45, v159
	v_add_f32_e32 v37, v47, v37
	v_mul_f32_e32 v160, 0x3fb8aa3b, v34
	v_exp_f32_e32 v34, v36
	v_add_f32_e32 v37, v40, v37
	v_mul_f32_e32 v38, 0x3fb8aa3b, v38
	v_add_f32_e32 v37, v41, v37
	v_mul_f32_e32 v39, 0x3fb8aa3b, v39
	v_exp_f32_e32 v38, v38
	v_add_f32_e32 v37, v44, v37
	v_mul_f32_e32 v32, 0x3fb8aa3b, v32
	v_exp_f32_e32 v39, v39
	v_add_f32_e32 v37, v45, v37
	v_mul_f32_e32 v33, 0x3fb8aa3b, v33
	v_exp_f32_e32 v32, v32
	v_add_f32_e32 v37, v34, v37
	v_exp_f32_e32 v33, v33
	v_add_f32_e32 v37, v35, v37
	v_exp_f32_e32 v36, v160
	v_add_f32_e32 v37, v38, v37
	v_add_f32_e32 v158, v39, v37
	v_exp_f32_e32 v37, v161
	v_add_f32_e32 v158, v32, v158
	v_add_f32_e32 v158, v33, v158
	v_add_f32_e32 v158, v36, v158
	v_add_f32_e32 v158, v37, v158
	ds_bpermute_b32 v159, v209, v158
	s_waitcnt lgkmcnt(0)
	v_add_f32_e32 v158, v158, v159
	ds_bpermute_b32 v159, v208, v158
	s_and_saveexec_b64 s[24:25], s[4:5]
	s_cbranch_execz .LBB0_1026
	s_waitcnt lgkmcnt(0)
	v_add_f32_e32 v158, v158, v159
	ds_write_b32 v191, v158 offset:4096
.LBB0_1026:
	s_or_b64 exec, exec, s[24:25]
	s_waitcnt lgkmcnt(0)
	s_nop 0
	s_waitcnt lgkmcnt(0)
	s_nop 0
	s_nop 0
	s_nop 0
	s_nop 0
	s_nop 0
	s_nop 0
	s_nop 0
	ds_read_b128 v[158:161], v202
	s_waitcnt lgkmcnt(0)
	s_nop 0
	s_nop 0
	s_waitcnt lgkmcnt(0)
	v_max_f32_e32 v161, v161, v161
	v_max_f32_e32 v160, v160, v160
	v_max_f32_e32 v160, v160, v161
	v_max3_f32 v158, v158, v159, v160
	s_waitcnt lgkmcnt(0)
	s_nop 0
	s_nop 0
	v_mov_b32_e32 v162, v252
	s_nop 0
	v_fma_f32 v28, v28, v162, -v158
	v_fma_f32 v29, v29, v162, -v158
	v_fma_f32 v26, v26, v162, -v158
	v_mul_f32_e32 v28, 0x3fb8aa3b, v28
	v_fma_f32 v30, v30, v162, -v158
	v_fma_f32 v31, v31, v162, -v158
	v_fma_f32 v24, v24, v162, -v158
	v_fma_f32 v25, v25, v162, -v158
	v_fma_f32 v27, v27, v162, -v158
	v_fma_f32 v20, v20, v162, -v158
	v_fma_f32 v21, v21, v162, -v158
	v_fma_f32 v22, v22, v162, -v158
	v_fma_f32 v23, v23, v162, -v158
	v_fma_f32 v16, v16, v162, -v158
	v_fma_f32 v17, v17, v162, -v158
	v_fma_f32 v18, v18, v162, -v158
	v_fma_f32 v19, v19, v162, -v158
	v_mul_f32_e32 v29, 0x3fb8aa3b, v29
	v_mul_f32_e32 v158, 0x3fb8aa3b, v26
	v_exp_f32_e32 v26, v28
	v_mul_f32_e32 v30, 0x3fb8aa3b, v30
	v_mul_f32_e32 v159, 0x3fb8aa3b, v27
	v_exp_f32_e32 v27, v29
	v_mul_f32_e32 v31, 0x3fb8aa3b, v31
	v_exp_f32_e32 v30, v30
	v_mul_f32_e32 v24, 0x3fb8aa3b, v24
	v_mul_f32_e32 v21, 0x3fb8aa3b, v21
	v_exp_f32_e32 v31, v31
	v_mul_f32_e32 v25, 0x3fb8aa3b, v25
	v_mul_f32_e32 v161, 0x3fb8aa3b, v19
	v_exp_f32_e32 v24, v24
	v_exp_f32_e32 v19, v21
	v_add_f32_e32 v21, 0, v26
	v_exp_f32_e32 v25, v25
	v_add_f32_e32 v21, v27, v21
	v_exp_f32_e32 v28, v158
	v_add_f32_e32 v21, v30, v21
	v_mul_f32_e32 v20, 0x3fb8aa3b, v20
	v_exp_f32_e32 v29, v159
	v_add_f32_e32 v21, v31, v21
	v_mul_f32_e32 v160, 0x3fb8aa3b, v18
	v_exp_f32_e32 v18, v20
	v_add_f32_e32 v21, v24, v21
	v_mul_f32_e32 v22, 0x3fb8aa3b, v22
	v_add_f32_e32 v21, v25, v21
	v_mul_f32_e32 v23, 0x3fb8aa3b, v23
	v_exp_f32_e32 v22, v22
	v_add_f32_e32 v21, v28, v21
	v_mul_f32_e32 v16, 0x3fb8aa3b, v16
	v_exp_f32_e32 v23, v23
	v_add_f32_e32 v21, v29, v21
	v_mul_f32_e32 v17, 0x3fb8aa3b, v17
	v_exp_f32_e32 v16, v16
	v_add_f32_e32 v21, v18, v21
	v_exp_f32_e32 v17, v17
	v_add_f32_e32 v21, v19, v21
	v_exp_f32_e32 v20, v160
	v_add_f32_e32 v21, v22, v21
	v_add_f32_e32 v158, v23, v21
	v_exp_f32_e32 v21, v161
	v_add_f32_e32 v158, v16, v158
	v_add_f32_e32 v158, v17, v158
	v_add_f32_e32 v158, v20, v158
	v_add_f32_e32 v158, v21, v158
	ds_bpermute_b32 v159, v209, v158
	s_waitcnt lgkmcnt(0)
	v_add_f32_e32 v158, v158, v159
	ds_bpermute_b32 v159, v208, v158
	s_and_saveexec_b64 s[24:25], s[4:5]
	s_cbranch_execz .LBB0_1028
	s_waitcnt lgkmcnt(0)
	v_add_f32_e32 v158, v158, v159
	ds_write_b32 v204, v158 offset:4096
; #define LAS __attribute__((address_space(3)))
; __device__ __forceinline__ v4u pack8(const f32x4 a, const f32x4 b) { v4u w; w.x = cvt_pk_bf16(a[0], a[1]); w.y = cvt_pk_bf16(a[2], a[3]); w.z = cvt_pk_bf16(b[0], b[1]); w.w = cvt_pk_bf16(b[2], b[3]); return w; }
;     __device__ __forceinline__ void operator()(const f32x4 (&acc_)[2][2][4][2], const pg8::Unit& u, int wr, int wc, int fr, int fq) const {
;     ...
;             for (int m = 0; m < 4; ++m) { const f32x4 x4 = *(const LAS f32x4*)(xch + (lrow0 + ai * 128 + m * 16) * 4); const float mrow = fmaxf(fmaxf(x4[0], x4[1]), fmaxf(x4[2], x4[3])), rs = row_rstd(ssq, row0 + ai * 128 + m * 16, fq); float sm = 0.f;
; #pragma unroll
;                 for (int bj = 0; bj < 2; ++bj)
; #pragma unroll
;                     for (int n = 0; n < 2; ++n) { f32x4 a = acc[ai][bj][m][n];
; #pragma unroll
;                         for (int i = 0; i < 4; ++i) { a[i] = __expf(a[i] * rs - mrow); sm += a[i]; }
;                         asm volatile("" ::: "memory");
;                         acc[ai][bj][m][n] = a; }
;                 sm += __shfl_xor(sm, 16); sm += __shfl_xor(sm, 32);
;                 if (fq == 0) xch[1024 + (lrow0 + ai * 128 + m * 16) * 4 + wc] = sm; }
;         asm volatile("s_waitcnt lgkmcnt(0)" ::: "memory"); __builtin_amdgcn_s_barrier(); asm volatile("" ::: "memory");
; #pragma unroll
;         for (int ai = 0; ai < 2; ++ai)
; #pragma unroll
;             for (int m = 0; m < 4; ++m) { const f32x4 x4 = *(const LAS f32x4*)(xch + 1024 + (lrow0 + ai * 128 + m * 16) * 4); const float inv = __builtin_amdgcn_rcpf((x4[0] + x4[1]) + (x4[2] + x4[3]));
; #pragma unroll
;                 for (int bj = 0; bj < 2; ++bj) *(v4u*)(P + (size_t)(row0 + ai * 128 + m * 16) * DM + u.pn * 256 + bj * 128 + wc * 32 + 8 * fq) = pack8(acc[ai][bj][m][0] * inv, acc[ai][bj][m][1] * inv); }
.LBB0_1028:
	s_or_b64 exec, exec, s[24:25]
	s_waitcnt lgkmcnt(0)
	s_nop 0
	s_waitcnt lgkmcnt(0)
	s_nop 0
	s_nop 0
	s_nop 0
	s_nop 0
	s_nop 0
	s_nop 0
	s_nop 0
	ds_read_b128 v[158:161], v205
	s_waitcnt lgkmcnt(0)
	s_nop 0
	s_nop 0
	s_waitcnt lgkmcnt(0)
	v_max_f32_e32 v161, v161, v161
	v_max_f32_e32 v160, v160, v160
	v_max_f32_e32 v160, v160, v161
	v_max3_f32 v158, v158, v159, v160
	s_waitcnt lgkmcnt(0)
	s_nop 0
	s_nop 0
	v_mov_b32_e32 v162, v253
	s_nop 0
	v_fma_f32 v12, v12, v162, -v158
	v_fma_f32 v13, v13, v162, -v158
	v_fma_f32 v10, v10, v162, -v158
	v_mul_f32_e32 v12, 0x3fb8aa3b, v12
	v_fma_f32 v14, v14, v162, -v158
	v_fma_f32 v15, v15, v162, -v158
	v_fma_f32 v8, v8, v162, -v158
	v_fma_f32 v9, v9, v162, -v158
	v_fma_f32 v11, v11, v162, -v158
	v_fma_f32 v4, v4, v162, -v158
	v_fma_f32 v5, v5, v162, -v158
	v_fma_f32 v6, v6, v162, -v158
	v_fma_f32 v7, v7, v162, -v158
	v_fma_f32 v0, v0, v162, -v158
	v_fma_f32 v1, v1, v162, -v158
	v_fma_f32 v2, v2, v162, -v158
	v_fma_f32 v3, v3, v162, -v158
	v_mul_f32_e32 v13, 0x3fb8aa3b, v13
	v_mul_f32_e32 v158, 0x3fb8aa3b, v10
	v_exp_f32_e32 v10, v12
	v_mul_f32_e32 v14, 0x3fb8aa3b, v14
	v_mul_f32_e32 v159, 0x3fb8aa3b, v11
	v_exp_f32_e32 v11, v13
	v_mul_f32_e32 v15, 0x3fb8aa3b, v15
	v_exp_f32_e32 v14, v14
	v_mul_f32_e32 v8, 0x3fb8aa3b, v8
	v_mul_f32_e32 v5, 0x3fb8aa3b, v5
	v_exp_f32_e32 v15, v15
	v_mul_f32_e32 v9, 0x3fb8aa3b, v9
	v_mul_f32_e32 v161, 0x3fb8aa3b, v3
	v_exp_f32_e32 v8, v8
	v_exp_f32_e32 v3, v5
	v_add_f32_e32 v5, 0, v10
	v_exp_f32_e32 v9, v9
	v_add_f32_e32 v5, v11, v5
	v_exp_f32_e32 v12, v158
	v_add_f32_e32 v5, v14, v5
	v_mul_f32_e32 v4, 0x3fb8aa3b, v4
	v_exp_f32_e32 v13, v159
	v_add_f32_e32 v5, v15, v5
	v_mul_f32_e32 v160, 0x3fb8aa3b, v2
	v_exp_f32_e32 v2, v4
	v_add_f32_e32 v5, v8, v5
	v_mul_f32_e32 v6, 0x3fb8aa3b, v6
	v_add_f32_e32 v5, v9, v5
	v_mul_f32_e32 v7, 0x3fb8aa3b, v7
	v_exp_f32_e32 v6, v6
	v_add_f32_e32 v5, v12, v5
	v_mul_f32_e32 v0, 0x3fb8aa3b, v0
	v_exp_f32_e32 v7, v7
	v_add_f32_e32 v5, v13, v5
	v_mul_f32_e32 v1, 0x3fb8aa3b, v1
	v_exp_f32_e32 v0, v0
	v_add_f32_e32 v5, v2, v5
	v_exp_f32_e32 v1, v1
	v_add_f32_e32 v5, v3, v5
	v_exp_f32_e32 v4, v160
	v_add_f32_e32 v5, v6, v5
	v_add_f32_e32 v158, v7, v5
	v_exp_f32_e32 v5, v161
	v_add_f32_e32 v158, v0, v158
	v_add_f32_e32 v158, v1, v158
	v_add_f32_e32 v158, v4, v158
	v_add_f32_e32 v158, v5, v158
	ds_bpermute_b32 v159, v209, v158
	s_waitcnt lgkmcnt(0)
	v_add_f32_e32 v158, v158, v159
	ds_bpermute_b32 v159, v208, v158
	s_and_saveexec_b64 s[24:25], s[4:5]
	s_cbranch_execz .LBB0_1030
	s_waitcnt lgkmcnt(0)
	v_add_f32_e32 v158, v158, v159
	ds_write_b32 v206, v158 offset:4096
.LBB0_1030:
	s_or_b64 exec, exec, s[24:25]
	s_waitcnt lgkmcnt(0)
	s_barrier
	v_add_u32_e32 v164, s75, v176
	s_waitcnt lgkmcnt(0)
	ds_read_b128 v[158:161], v164
	s_lshl_b32 s22, s22, 8
	s_ashr_i32 s23, s22, 31
	v_lshlrev_b64 v[142:143], 11, v[142:143]
	s_lshl_b64 s[22:23], s[22:23], 1
	s_waitcnt lgkmcnt(0)
	v_mov_b32_e32 v162, v159
	v_mov_b32_e32 v163, v160
	v_mov_b32_e32 v159, v161
	v_pk_add_f32 v[158:159], v[162:163], v[158:159]
	s_andn2_b64 vcc, exec, s[6:7]
	v_add_f32_e32 v158, v158, v159
	v_rcp_f32_e32 v158, v158
	s_mov_b64 s[6:7], -1
	v_pk_mul_f32 v[122:123], v[122:123], v[158:159] op_sel_hi:[1,0]
	v_pk_mul_f32 v[124:125], v[124:125], v[158:159] op_sel_hi:[1,0]
	v_pk_mul_f32 v[160:161], v[120:121], v[158:159] op_sel_hi:[1,0]
	v_cvt_pk_bf16_f32 v120, v122, v123
	v_cvt_pk_bf16_f32 v123, v124, v125
	v_lshl_add_u64 v[124:125], s[10:11], 0, v[142:143]
	v_lshl_add_u64 v[124:125], v[124:125], 0, s[22:23]
	v_pk_mul_f32 v[126:127], v[126:127], v[158:159] op_sel_hi:[1,0]
	v_lshl_add_u64 v[124:125], v[124:125], 0, s[68:69]
	v_cvt_pk_bf16_f32 v121, v126, v127
	v_cvt_pk_bf16_f32 v122, v160, v161
	v_lshl_add_u64 v[124:125], v[124:125], 0, v[192:193]
	global_store_dwordx4 v[124:125], v[120:123], off
	v_pk_mul_f32 v[118:119], v[118:119], v[158:159] op_sel_hi:[1,0]
	v_pk_mul_f32 v[114:115], v[114:115], v[158:159] op_sel_hi:[1,0]
	v_pk_mul_f32 v[116:117], v[116:117], v[158:159] op_sel_hi:[1,0]
	v_pk_mul_f32 v[120:121], v[112:113], v[158:159] op_sel_hi:[1,0]
	v_cvt_pk_bf16_f32 v112, v114, v115
	v_cvt_pk_bf16_f32 v113, v118, v119
	v_cvt_pk_bf16_f32 v114, v120, v121
	v_cvt_pk_bf16_f32 v115, v116, v117
	global_store_dwordx4 v[124:125], v[112:115], off offset:256
	s_nop 1
	v_add_u32_e32 v112, s75, v177
	ds_read_b128 v[112:115], v112
	s_waitcnt lgkmcnt(0)
	v_mov_b32_e32 v116, v113
	v_mov_b32_e32 v117, v114
	v_mov_b32_e32 v113, v115
	v_pk_add_f32 v[112:113], v[116:117], v[112:113]
	v_lshlrev_b64 v[114:115], 11, v[144:145]
	v_add_f32_e32 v112, v112, v113
	v_rcp_f32_e32 v112, v112
	s_nop 0
	v_pk_mul_f32 v[106:107], v[106:107], v[112:113] op_sel_hi:[1,0]
	v_pk_mul_f32 v[108:109], v[108:109], v[112:113] op_sel_hi:[1,0]
	v_pk_mul_f32 v[116:117], v[104:105], v[112:113] op_sel_hi:[1,0]
	v_cvt_pk_bf16_f32 v104, v106, v107
	v_cvt_pk_bf16_f32 v107, v108, v109
	v_lshl_add_u64 v[108:109], s[10:11], 0, v[114:115]
	v_lshl_add_u64 v[108:109], v[108:109], 0, s[22:23]
	v_pk_mul_f32 v[110:111], v[110:111], v[112:113] op_sel_hi:[1,0]
	v_lshl_add_u64 v[108:109], v[108:109], 0, s[68:69]
	v_cvt_pk_bf16_f32 v105, v110, v111
	v_cvt_pk_bf16_f32 v106, v116, v117
	v_lshl_add_u64 v[108:109], v[108:109], 0, v[192:193]
	global_store_dwordx4 v[108:109], v[104:107], off
	v_pk_mul_f32 v[102:103], v[102:103], v[112:113] op_sel_hi:[1,0]
	v_pk_mul_f32 v[98:99], v[98:99], v[112:113] op_sel_hi:[1,0]
	v_pk_mul_f32 v[100:101], v[100:101], v[112:113] op_sel_hi:[1,0]
	v_pk_mul_f32 v[104:105], v[96:97], v[112:113] op_sel_hi:[1,0]
	v_cvt_pk_bf16_f32 v96, v98, v99
	v_cvt_pk_bf16_f32 v97, v102, v103
	v_cvt_pk_bf16_f32 v98, v104, v105
	v_cvt_pk_bf16_f32 v99, v100, v101
	global_store_dwordx4 v[108:109], v[96:99], off offset:256
	s_nop 1
	v_add_u32_e32 v96, s75, v254
	ds_read_b128 v[96:99], v96
	s_waitcnt lgkmcnt(0)
; #define LAS __attribute__((address_space(3)))
; __device__ __forceinline__ v4u pack8(const f32x4 a, const f32x4 b) { v4u w; w.x = cvt_pk_bf16(a[0], a[1]); w.y = cvt_pk_bf16(a[2], a[3]); w.z = cvt_pk_bf16(b[0], b[1]); w.w = cvt_pk_bf16(b[2], b[3]); return w; }
;     __device__ __forceinline__ void operator()(const f32x4 (&acc_)[2][2][4][2], const pg8::Unit& u, int wr, int wc, int fr, int fq) const {
;     ...
; #pragma unroll
;         for (int ai = 0; ai < 2; ++ai)
; #pragma unroll
;             for (int m = 0; m < 4; ++m) { const f32x4 x4 = *(const LAS f32x4*)(xch + 1024 + (lrow0 + ai * 128 + m * 16) * 4); const float inv = __builtin_amdgcn_rcpf((x4[0] + x4[1]) + (x4[2] + x4[3]));
; #pragma unroll
;                 for (int bj = 0; bj < 2; ++bj) *(v4u*)(P + (size_t)(row0 + ai * 128 + m * 16) * DM + u.pn * 256 + bj * 128 + wc * 32 + 8 * fq) = pack8(acc[ai][bj][m][0] * inv, acc[ai][bj][m][1] * inv); }
	v_mov_b32_e32 v100, v97
	v_mov_b32_e32 v101, v98
	v_mov_b32_e32 v97, v99
	v_pk_add_f32 v[96:97], v[100:101], v[96:97]
	v_lshlrev_b64 v[98:99], 11, v[146:147]
	v_add_f32_e32 v96, v96, v97
	v_rcp_f32_e32 v96, v96
	s_nop 0
	v_pk_mul_f32 v[90:91], v[90:91], v[96:97] op_sel_hi:[1,0]
	v_pk_mul_f32 v[92:93], v[92:93], v[96:97] op_sel_hi:[1,0]
	v_pk_mul_f32 v[100:101], v[88:89], v[96:97] op_sel_hi:[1,0]
	v_cvt_pk_bf16_f32 v88, v90, v91
	v_cvt_pk_bf16_f32 v91, v92, v93
	v_lshl_add_u64 v[92:93], s[10:11], 0, v[98:99]
	v_lshl_add_u64 v[92:93], v[92:93], 0, s[22:23]
	v_pk_mul_f32 v[94:95], v[94:95], v[96:97] op_sel_hi:[1,0]
	v_lshl_add_u64 v[92:93], v[92:93], 0, s[68:69]
	v_cvt_pk_bf16_f32 v89, v94, v95
	v_cvt_pk_bf16_f32 v90, v100, v101
	v_lshl_add_u64 v[92:93], v[92:93], 0, v[192:193]
	global_store_dwordx4 v[92:93], v[88:91], off
	v_pk_mul_f32 v[86:87], v[86:87], v[96:97] op_sel_hi:[1,0]
	v_pk_mul_f32 v[82:83], v[82:83], v[96:97] op_sel_hi:[1,0]
	v_pk_mul_f32 v[84:85], v[84:85], v[96:97] op_sel_hi:[1,0]
	v_pk_mul_f32 v[88:89], v[80:81], v[96:97] op_sel_hi:[1,0]
	v_cvt_pk_bf16_f32 v80, v82, v83
	v_cvt_pk_bf16_f32 v81, v86, v87
	v_cvt_pk_bf16_f32 v82, v88, v89
	v_cvt_pk_bf16_f32 v83, v84, v85
	global_store_dwordx4 v[92:93], v[80:83], off offset:256
	s_nop 1
	v_add_u32_e32 v80, s75, v213
	ds_read_b128 v[80:83], v80
	s_waitcnt lgkmcnt(0)
	v_mov_b32_e32 v84, v81
	v_mov_b32_e32 v85, v82
	v_mov_b32_e32 v81, v83
	v_pk_add_f32 v[80:81], v[84:85], v[80:81]
	v_lshlrev_b64 v[82:83], 11, v[148:149]
	v_add_f32_e32 v80, v80, v81
	v_rcp_f32_e32 v80, v80
	s_nop 0
	v_pk_mul_f32 v[74:75], v[74:75], v[80:81] op_sel_hi:[1,0]
	v_pk_mul_f32 v[76:77], v[76:77], v[80:81] op_sel_hi:[1,0]
	v_pk_mul_f32 v[84:85], v[72:73], v[80:81] op_sel_hi:[1,0]
	v_cvt_pk_bf16_f32 v72, v74, v75
	v_cvt_pk_bf16_f32 v75, v76, v77
	v_lshl_add_u64 v[76:77], s[10:11], 0, v[82:83]
	v_lshl_add_u64 v[76:77], v[76:77], 0, s[22:23]
	v_pk_mul_f32 v[78:79], v[78:79], v[80:81] op_sel_hi:[1,0]
	v_lshl_add_u64 v[76:77], v[76:77], 0, s[68:69]
	v_cvt_pk_bf16_f32 v73, v78, v79
	v_cvt_pk_bf16_f32 v74, v84, v85
	v_lshl_add_u64 v[76:77], v[76:77], 0, v[192:193]
	global_store_dwordx4 v[76:77], v[72:75], off
	v_pk_mul_f32 v[70:71], v[70:71], v[80:81] op_sel_hi:[1,0]
	v_pk_mul_f32 v[66:67], v[66:67], v[80:81] op_sel_hi:[1,0]
	v_pk_mul_f32 v[68:69], v[68:69], v[80:81] op_sel_hi:[1,0]
	v_pk_mul_f32 v[72:73], v[64:65], v[80:81] op_sel_hi:[1,0]
	v_cvt_pk_bf16_f32 v64, v66, v67
	v_cvt_pk_bf16_f32 v65, v70, v71
	v_cvt_pk_bf16_f32 v66, v72, v73
	v_cvt_pk_bf16_f32 v67, v68, v69
	global_store_dwordx4 v[76:77], v[64:67], off offset:256
	ds_read_b128 v[64:67], v164 offset:2048
	s_waitcnt lgkmcnt(0)
	v_mov_b32_e32 v68, v65
	v_mov_b32_e32 v69, v66
	v_mov_b32_e32 v65, v67
	v_pk_add_f32 v[64:65], v[68:69], v[64:65]
	v_lshlrev_b64 v[66:67], 11, v[150:151]
	v_add_f32_e32 v64, v64, v65
	v_rcp_f32_e32 v64, v64
	s_nop 0
	v_pk_mul_f32 v[58:59], v[58:59], v[64:65] op_sel_hi:[1,0]
	v_pk_mul_f32 v[60:61], v[60:61], v[64:65] op_sel_hi:[1,0]
	v_pk_mul_f32 v[68:69], v[56:57], v[64:65] op_sel_hi:[1,0]
	v_cvt_pk_bf16_f32 v56, v58, v59
	v_cvt_pk_bf16_f32 v59, v60, v61
	v_lshl_add_u64 v[60:61], s[10:11], 0, v[66:67]
	v_lshl_add_u64 v[60:61], v[60:61], 0, s[22:23]
	v_pk_mul_f32 v[62:63], v[62:63], v[64:65] op_sel_hi:[1,0]
	v_lshl_add_u64 v[60:61], v[60:61], 0, s[68:69]
	v_cvt_pk_bf16_f32 v57, v62, v63
	v_cvt_pk_bf16_f32 v58, v68, v69
	v_lshl_add_u64 v[60:61], v[60:61], 0, v[192:193]
	global_store_dwordx4 v[60:61], v[56:59], off
	v_pk_mul_f32 v[54:55], v[54:55], v[64:65] op_sel_hi:[1,0]
	v_pk_mul_f32 v[50:51], v[50:51], v[64:65] op_sel_hi:[1,0]
	v_pk_mul_f32 v[52:53], v[52:53], v[64:65] op_sel_hi:[1,0]
	v_pk_mul_f32 v[56:57], v[48:49], v[64:65] op_sel_hi:[1,0]
	v_cvt_pk_bf16_f32 v48, v50, v51
	v_cvt_pk_bf16_f32 v49, v54, v55
	v_cvt_pk_bf16_f32 v50, v56, v57
	v_cvt_pk_bf16_f32 v51, v52, v53
	global_store_dwordx4 v[60:61], v[48:51], off offset:256
	ds_read_b128 v[48:51], v164 offset:2304
	s_waitcnt lgkmcnt(0)
; #define LAS __attribute__((address_space(3)))
; __device__ __forceinline__ v4u pack8(const f32x4 a, const f32x4 b) { v4u w; w.x = cvt_pk_bf16(a[0], a[1]); w.y = cvt_pk_bf16(a[2], a[3]); w.z = cvt_pk_bf16(b[0], b[1]); w.w = cvt_pk_bf16(b[2], b[3]); return w; }
;     __device__ __forceinline__ void operator()(const f32x4 (&acc_)[2][2][4][2], const pg8::Unit& u, int wr, int wc, int fr, int fq) const {
;     ...
; #pragma unroll
;         for (int ai = 0; ai < 2; ++ai)
; #pragma unroll
;             for (int m = 0; m < 4; ++m) { const f32x4 x4 = *(const LAS f32x4*)(xch + 1024 + (lrow0 + ai * 128 + m * 16) * 4); const float inv = __builtin_amdgcn_rcpf((x4[0] + x4[1]) + (x4[2] + x4[3]));
; #pragma unroll
;                 for (int bj = 0; bj < 2; ++bj) *(v4u*)(P + (size_t)(row0 + ai * 128 + m * 16) * DM + u.pn * 256 + bj * 128 + wc * 32 + 8 * fq) = pack8(acc[ai][bj][m][0] * inv, acc[ai][bj][m][1] * inv); }
;         asm volatile("s_waitcnt lgkmcnt(0)" ::: "memory"); __builtin_amdgcn_s_barrier(); asm volatile("" ::: "memory");
	v_mov_b32_e32 v52, v49
	v_mov_b32_e32 v53, v50
	v_mov_b32_e32 v49, v51
	v_pk_add_f32 v[48:49], v[52:53], v[48:49]
	v_lshlrev_b64 v[50:51], 11, v[152:153]
	v_add_f32_e32 v48, v48, v49
	v_rcp_f32_e32 v48, v48
	s_nop 0
	v_pk_mul_f32 v[42:43], v[42:43], v[48:49] op_sel_hi:[1,0]
	v_pk_mul_f32 v[44:45], v[44:45], v[48:49] op_sel_hi:[1,0]
	v_pk_mul_f32 v[52:53], v[40:41], v[48:49] op_sel_hi:[1,0]
	v_cvt_pk_bf16_f32 v40, v42, v43
	v_cvt_pk_bf16_f32 v43, v44, v45
	v_lshl_add_u64 v[44:45], s[10:11], 0, v[50:51]
	v_lshl_add_u64 v[44:45], v[44:45], 0, s[22:23]
	v_pk_mul_f32 v[46:47], v[46:47], v[48:49] op_sel_hi:[1,0]
	v_lshl_add_u64 v[44:45], v[44:45], 0, s[68:69]
	v_cvt_pk_bf16_f32 v41, v46, v47
	v_cvt_pk_bf16_f32 v42, v52, v53
	v_lshl_add_u64 v[44:45], v[44:45], 0, v[192:193]
	global_store_dwordx4 v[44:45], v[40:43], off
	v_pk_mul_f32 v[38:39], v[38:39], v[48:49] op_sel_hi:[1,0]
	v_pk_mul_f32 v[34:35], v[34:35], v[48:49] op_sel_hi:[1,0]
	v_pk_mul_f32 v[36:37], v[36:37], v[48:49] op_sel_hi:[1,0]
	v_pk_mul_f32 v[40:41], v[32:33], v[48:49] op_sel_hi:[1,0]
	v_cvt_pk_bf16_f32 v32, v34, v35
	v_cvt_pk_bf16_f32 v33, v38, v39
	v_cvt_pk_bf16_f32 v34, v40, v41
	v_cvt_pk_bf16_f32 v35, v36, v37
	global_store_dwordx4 v[44:45], v[32:35], off offset:256
	ds_read_b128 v[32:35], v164 offset:2560
	s_waitcnt lgkmcnt(0)
	v_mov_b32_e32 v36, v33
	v_mov_b32_e32 v37, v34
	v_mov_b32_e32 v33, v35
	v_pk_add_f32 v[32:33], v[36:37], v[32:33]
	v_lshlrev_b64 v[34:35], 11, v[154:155]
	v_add_f32_e32 v32, v32, v33
	v_rcp_f32_e32 v32, v32
	s_nop 0
	v_pk_mul_f32 v[26:27], v[26:27], v[32:33] op_sel_hi:[1,0]
	v_pk_mul_f32 v[28:29], v[28:29], v[32:33] op_sel_hi:[1,0]
	v_pk_mul_f32 v[36:37], v[24:25], v[32:33] op_sel_hi:[1,0]
	v_cvt_pk_bf16_f32 v24, v26, v27
	v_cvt_pk_bf16_f32 v27, v28, v29
	v_lshl_add_u64 v[28:29], s[10:11], 0, v[34:35]
	v_lshl_add_u64 v[28:29], v[28:29], 0, s[22:23]
	v_pk_mul_f32 v[30:31], v[30:31], v[32:33] op_sel_hi:[1,0]
	v_lshl_add_u64 v[28:29], v[28:29], 0, s[68:69]
	v_cvt_pk_bf16_f32 v25, v30, v31
	v_cvt_pk_bf16_f32 v26, v36, v37
	v_lshl_add_u64 v[28:29], v[28:29], 0, v[192:193]
	global_store_dwordx4 v[28:29], v[24:27], off
	v_pk_mul_f32 v[22:23], v[22:23], v[32:33] op_sel_hi:[1,0]
	v_pk_mul_f32 v[18:19], v[18:19], v[32:33] op_sel_hi:[1,0]
	v_pk_mul_f32 v[20:21], v[20:21], v[32:33] op_sel_hi:[1,0]
	v_pk_mul_f32 v[24:25], v[16:17], v[32:33] op_sel_hi:[1,0]
	v_cvt_pk_bf16_f32 v16, v18, v19
	v_cvt_pk_bf16_f32 v17, v22, v23
	v_cvt_pk_bf16_f32 v18, v24, v25
	v_cvt_pk_bf16_f32 v19, v20, v21
	global_store_dwordx4 v[28:29], v[16:19], off offset:256
	ds_read_b128 v[16:19], v164 offset:2816
	s_waitcnt lgkmcnt(0)
	v_mov_b32_e32 v20, v17
	v_mov_b32_e32 v21, v18
	v_mov_b32_e32 v17, v19
	v_pk_add_f32 v[16:17], v[20:21], v[16:17]
	v_lshlrev_b64 v[18:19], 11, v[156:157]
	v_add_f32_e32 v16, v16, v17
	v_rcp_f32_e32 v16, v16
	s_nop 0
	v_pk_mul_f32 v[10:11], v[10:11], v[16:17] op_sel_hi:[1,0]
	v_pk_mul_f32 v[12:13], v[12:13], v[16:17] op_sel_hi:[1,0]
	v_pk_mul_f32 v[20:21], v[8:9], v[16:17] op_sel_hi:[1,0]
	v_cvt_pk_bf16_f32 v8, v10, v11
	v_cvt_pk_bf16_f32 v11, v12, v13
	v_lshl_add_u64 v[12:13], s[10:11], 0, v[18:19]
	v_lshl_add_u64 v[12:13], v[12:13], 0, s[22:23]
	v_pk_mul_f32 v[14:15], v[14:15], v[16:17] op_sel_hi:[1,0]
	v_lshl_add_u64 v[12:13], v[12:13], 0, s[68:69]
	v_cvt_pk_bf16_f32 v9, v14, v15
	v_cvt_pk_bf16_f32 v10, v20, v21
	v_lshl_add_u64 v[12:13], v[12:13], 0, v[192:193]
	global_store_dwordx4 v[12:13], v[8:11], off
	v_pk_mul_f32 v[6:7], v[6:7], v[16:17] op_sel_hi:[1,0]
	v_pk_mul_f32 v[2:3], v[2:3], v[16:17] op_sel_hi:[1,0]
	v_pk_mul_f32 v[4:5], v[4:5], v[16:17] op_sel_hi:[1,0]
	v_pk_mul_f32 v[8:9], v[0:1], v[16:17] op_sel_hi:[1,0]
	v_cvt_pk_bf16_f32 v0, v2, v3
	v_cvt_pk_bf16_f32 v1, v6, v7
	v_cvt_pk_bf16_f32 v2, v8, v9
	v_cvt_pk_bf16_f32 v3, v4, v5
	global_store_dwordx4 v[12:13], v[0:3], off offset:256
	s_waitcnt lgkmcnt(0)
	s_barrier
	s_cbranch_vccnz .LBB0_987
	s_andn2_b64 vcc, exec, s[8:9]
	s_cbranch_vccnz .LBB0_986
	s_barrier
	s_branch .LBB0_986
